# mixnorm and final row loops: norm weights hoisted out of the loop, next row's loads prefetched (counted waits leave the row stores in flight)
# speedup vs baseline: 1.0139x; 1.0139x over previous
; __device__ void phase_mixnorm(const KP& p, int l) {
;   int tid_ = threadIdx.x; asm volatile("" : "+v"(tid_));
;   const int lane = tid_ & 63, w = tid_ >> 6;
;   bfr* mix = (bfr*)(p.ws + OFF_MIX);
;   const bfr* proj = (const bfr*)(p.ws + OFF_U);
;   for (int row = p.bid * 8 + w; row < T_ROWS; row += p.nblk * 8) {
;     bfr* mp = mix + (size_t)row * DM + lane * 16;
;     u32x4 v0 = *(const u32x4*)mp, v1 = *(const u32x4*)(mp + 8);
;     float x[16];
; #pragma unroll
;     for (int e = 0; e < 4; ++e) {
;       x[e * 2] = __uint_as_float(v0[e] << 16); x[e * 2 + 1] = __uint_as_float(v0[e] & 0xffff0000u);
;       x[8 + e * 2] = __uint_as_float(v1[e] << 16); x[8 + e * 2 + 1] = __uint_as_float(v1[e] & 0xffff0000u);
;     }
;     float ss = 0.f;
; #pragma unroll
;     for (int e = 0; e < 16; ++e) ss += x[e] * x[e];
;     ss += __shfl_xor(ss, 1); ss += __shfl_xor(ss, 2); ss += __shfl_xor(ss, 4);
;     float s8 = __shfl_xor(ss, 8);
;     float r;
;     if (lane < 32) r = rsqrtf((ss + s8) * (1.f / 256.f) + EPSF);
;     else r = rsqrtf(ss * (1.f / 128.f) + EPSF);
;     float o[16];
;     if (lane < 32) {
;       const float* nw = p.in[17] + l * 512 + lane * 16;
; #pragma unroll
;       for (int e = 0; e < 16; ++e) o[e] = x[e] * r * nw[e];
;     } else {
;       int cg0 = (lane - 32) * 16;
;       const float* nw = p.in[19] + l * 512 + cg0;
;       const bfr* gp = proj + (size_t)row * NIN + 3072 + cg0;
;       u32x4 g0 = *(const u32x4*)gp, g1 = *(const u32x4*)(gp + 8);
.LBB0_309:
	v_readlane_b32 s0, v255, 61
	s_cmp_gt_i32 s0, 5
	s_mov_b64 s[0:1], -1
	s_cbranch_scc0 .LBB0_318
	v_mov_b32_e32 v0, v156
	v_readlane_b32 s0, v255, 42
	s_lshl_b32 s50, s0, 3
	s_waitcnt vmcnt(0)
	v_ashrrev_i32_e32 v2, 6, v0
	v_add_u32_e32 v50, s50, v2
	s_mov_b32 s0, 0x8400
	v_cmp_gt_i32_e32 vcc, s0, v50
	s_and_saveexec_b64 s[0:1], vcc
	v_readlane_b32 s52, v255, 43
	v_readlane_b32 s53, v255, 44
	s_cbranch_execz .LBB0_317
	v_and_b32_e32 v3, 64, v164
	v_and_b32_e32 v6, 63, v0
	v_xor_b32_e32 v0, 1, v164
	v_add_u32_e32 v3, 64, v3
	v_cmp_lt_i32_e32 vcc, v0, v3
	s_lshl_b32 s2, s92, 9
	s_ashr_i32 s3, s2, 31
	v_cndmask_b32_e32 v0, v164, v0, vcc
	v_lshlrev_b32_e32 v51, 2, v0
	v_xor_b32_e32 v0, 2, v164
	v_cmp_lt_i32_e32 vcc, v0, v3
	v_readlane_b32 s16, v255, 24
	s_lshl_b32 s46, s52, 3
	v_cndmask_b32_e32 v0, v164, v0, vcc
	v_lshlrev_b32_e32 v52, 2, v0
	v_xor_b32_e32 v0, 4, v164
	v_cmp_lt_i32_e32 vcc, v0, v3
	s_lshl_b64 s[2:3], s[2:3], 2
	v_readlane_b32 s22, v255, 30
	v_cndmask_b32_e32 v0, v164, v0, vcc
	v_lshlrev_b32_e32 v53, 2, v0
	v_xor_b32_e32 v0, 8, v164
	v_cmp_lt_i32_e32 vcc, v0, v3
	v_readlane_b32 s23, v255, 31
	s_add_u32 s14, s22, s2
	v_cndmask_b32_e32 v0, v164, v0, vcc
	v_readlane_b32 s18, v255, 26
	s_addc_u32 s15, s23, s3
	v_lshlrev_b32_e32 v54, 2, v0
	v_mov_b32_e32 v0, 0xfffffe00
	v_readlane_b32 s19, v255, 27
	s_add_u32 s2, s18, s2
	v_lshl_add_u32 v0, v6, 4, v0
	s_addc_u32 s3, s19, s3
	v_lshlrev_b32_e32 v4, 6, v6
	v_mov_b32_e32 v5, v1
	v_ashrrev_i32_e32 v3, 31, v2
	s_ashr_i32 s51, s50, 31
	v_lshl_add_u64 v[22:23], v[0:1], 2, s[14:15]
	v_lshl_add_u64 v[24:25], s[2:3], 0, v[4:5]
	v_lshl_add_u64 v[2:3], v[2:3], 0, s[50:51]
	v_lshlrev_b64 v[4:5], 1, v[0:1]
	s_movk_i32 s14, 0x1c00
	v_mad_u64_u32 v[26:27], s[2:3], v2, s14, v[4:5]
	s_ashr_i32 s47, s46, 31
	v_lshlrev_b64 v[28:29], 11, v[2:3]
	v_cmp_gt_u32_e64 s[38:39], 32, v6
	v_cmp_lt_u32_e64 s[40:41], 31, v6
	v_mad_i32_i24 v27, v3, s14, v27
	s_mul_i32 s50, s52, 0xe000
	s_mul_hi_i32 s51, s46, 0x1c00
	v_lshl_or_b32 v28, v6, 5, v28
	s_lshl_b64 s[52:53], s[46:47], 11
	s_mov_b64 s[74:75], 0
	v_readlane_b32 s17, v255, 25
	v_readlane_b32 s20, v255, 28
	v_readlane_b32 s21, v255, 29
	v_readlane_b32 s24, v255, 32
	v_readlane_b32 s25, v255, 33
	v_readlane_b32 s26, v255, 34
	v_readlane_b32 s27, v255, 35
	v_readlane_b32 s28, v255, 36
	v_readlane_b32 s29, v255, 37
	v_readlane_b32 s30, v255, 38
	v_readlane_b32 s31, v255, 39
	v_readlane_b32 s100, v255, 45
	v_readlane_b32 s101, v255, 46
	s_nop 3
	s_add_u32 s100, s100, 0x432a800
	s_addc_u32 s101, s101, 0
	s_mov_b64 s[98:99], exec
	s_and_b64 exec, s[98:99], s[40:41]
	global_load_dwordx4 v[64:67], v[22:23], off
	global_load_dwordx4 v[68:71], v[22:23], off offset:16
	global_load_dwordx4 v[72:75], v[22:23], off offset:32
	global_load_dwordx4 v[76:79], v[22:23], off offset:48
	s_andn2_b64 exec, s[98:99], s[40:41]
	global_load_dwordx4 v[64:67], v[24:25], off
	global_load_dwordx4 v[68:71], v[24:25], off offset:16
	global_load_dwordx4 v[72:75], v[24:25], off offset:32
	global_load_dwordx4 v[76:79], v[24:25], off offset:48
	s_mov_b64 exec, s[98:99]
	v_readlane_b32 s2, v255, 45
	v_readlane_b32 s3, v255, 46
	s_nop 3
	s_add_u32 s2, s2, 0x12a29000
	s_addc_u32 s3, s3, 0
	v_lshl_add_u64 v[106:107], v[28:29], 0, s[2:3]
	global_load_dwordx4 v[88:91], v[106:107], off
	global_load_dwordx4 v[92:95], v[106:107], off offset:16
	v_lshl_add_u64 v[104:105], v[26:27], 0, s[100:101]
	s_and_b64 exec, s[98:99], s[40:41]
	global_load_dwordx4 v[80:83], v[104:105], off
	global_load_dwordx4 v[84:87], v[104:105], off offset:16
	s_mov_b64 exec, s[98:99]
	global_load_dword v108, v[106:107], off
	global_load_dword v108, v[106:107], off
	s_branch .LBB0_313

; __device__ void phase_mixnorm(const KP& p, int l) {
;     ...
;   for (int row = p.bid * 8 + w; row < T_ROWS; row += p.nblk * 8) {
;     bfr* mp = mix + (size_t)row * DM + lane * 16;
;     u32x4 v0 = *(const u32x4*)mp, v1 = *(const u32x4*)(mp + 8);
;     float x[16];
; #pragma unroll
;     for (int e = 0; e < 4; ++e) {
;       x[e * 2] = __uint_as_float(v0[e] << 16); x[e * 2 + 1] = __uint_as_float(v0[e] & 0xffff0000u);
;       x[8 + e * 2] = __uint_as_float(v1[e] << 16); x[8 + e * 2 + 1] = __uint_as_float(v1[e] & 0xffff0000u);
;     }
;     float ss = 0.f;
; #pragma unroll
;     for (int e = 0; e < 16; ++e) ss += x[e] * x[e];
;     ss += __shfl_xor(ss, 1); ss += __shfl_xor(ss, 2); ss += __shfl_xor(ss, 4);
;     float s8 = __shfl_xor(ss, 8);
;     float r;
;     if (lane < 32) r = rsqrtf((ss + s8) * (1.f / 256.f) + EPSF);
;     else r = rsqrtf(ss * (1.f / 128.f) + EPSF);
.LBB0_313:
	v_readlane_b32 s2, v255, 45
	v_readlane_b32 s3, v255, 46
	s_nop 1
	v_lshl_add_u64 v[30:31], s[2:3], 0, v[28:29]
	s_mov_b64 s[2:3], 0x12a29000
	v_lshl_add_u64 v[32:33], v[30:31], 0, s[2:3]
	s_waitcnt lgkmcnt(0)
	s_mov_b32 s2, 0x800000
	s_waitcnt vmcnt(2)
	v_mov_b32_e32 v2, v88
	v_mov_b32_e32 v3, v89
	v_mov_b32_e32 v4, v90
	v_mov_b32_e32 v5, v91
	v_mov_b32_e32 v8, v92
	v_mov_b32_e32 v9, v93
	v_mov_b32_e32 v10, v94
	v_mov_b32_e32 v11, v95
	v_mov_b32_e32 v96, v80
	v_mov_b32_e32 v97, v81
	v_mov_b32_e32 v98, v82
	v_mov_b32_e32 v99, v83
	v_mov_b32_e32 v100, v84
	v_mov_b32_e32 v101, v85
	v_mov_b32_e32 v102, v86
	v_mov_b32_e32 v103, v87
	v_lshl_add_u64 v[104:105], v[32:33], 0, s[52:53]
	global_load_dwordx4 v[88:91], v[104:105], off
	global_load_dwordx4 v[92:95], v[104:105], off offset:16
	v_lshl_add_u64 v[104:105], v[26:27], 0, s[50:51]
	v_lshl_add_u64 v[104:105], v[104:105], 0, s[100:101]
	s_mov_b64 s[98:99], exec
	s_and_b64 exec, s[98:99], s[40:41]
	global_load_dwordx4 v[80:83], v[104:105], off
	global_load_dwordx4 v[84:87], v[104:105], off offset:16
	s_mov_b64 exec, s[98:99]
	v_lshlrev_b32_e32 v6, 16, v2
	v_and_b32_e32 v7, 0xffff0000, v2
	v_lshlrev_b32_e32 v48, 16, v3
	v_and_b32_e32 v49, 0xffff0000, v3
	v_pk_mul_f32 v[2:3], v[6:7], v[6:7]
	v_lshlrev_b32_e32 v46, 16, v4
	v_and_b32_e32 v47, 0xffff0000, v4
	v_lshlrev_b32_e32 v44, 16, v5
	v_and_b32_e32 v45, 0xffff0000, v5
	v_pk_mul_f32 v[4:5], v[48:49], v[48:49]
	v_add_f32_e32 v0, v2, v3
	v_add_f32_e32 v0, v4, v0
	v_lshlrev_b32_e32 v42, 16, v8
	v_and_b32_e32 v43, 0xffff0000, v8
	v_lshlrev_b32_e32 v40, 16, v9
	v_and_b32_e32 v41, 0xffff0000, v9
	v_pk_mul_f32 v[8:9], v[46:47], v[46:47]
	v_add_f32_e32 v0, v5, v0
	v_add_f32_e32 v0, v8, v0
	v_lshlrev_b32_e32 v36, 16, v10
	v_and_b32_e32 v37, 0xffff0000, v10
	v_lshlrev_b32_e32 v34, 16, v11
	v_and_b32_e32 v35, 0xffff0000, v11
	v_pk_mul_f32 v[10:11], v[44:45], v[44:45]
	v_add_f32_e32 v0, v9, v0
	v_add_f32_e32 v0, v10, v0
	v_pk_mul_f32 v[12:13], v[42:43], v[42:43]
	v_add_f32_e32 v0, v11, v0
	v_add_f32_e32 v0, v12, v0
	v_pk_mul_f32 v[14:15], v[40:41], v[40:41]
	v_add_f32_e32 v0, v13, v0
	v_add_f32_e32 v0, v14, v0
	v_pk_mul_f32 v[16:17], v[36:37], v[36:37]
	v_add_f32_e32 v0, v15, v0
	v_add_f32_e32 v0, v16, v0
	v_pk_mul_f32 v[18:19], v[34:35], v[34:35]
	v_add_f32_e32 v0, v17, v0
	v_add_f32_e32 v0, v18, v0
	v_add_f32_e32 v0, v19, v0
	ds_bpermute_b32 v2, v51, v0
	s_waitcnt lgkmcnt(0)
	v_add_f32_e32 v0, v0, v2
	ds_bpermute_b32 v2, v52, v0
	s_waitcnt lgkmcnt(0)
	v_add_f32_e32 v0, v0, v2
	ds_bpermute_b32 v2, v53, v0
	s_waitcnt lgkmcnt(0)
	v_add_f32_e32 v0, v0, v2
	ds_bpermute_b32 v2, v54, v0
	v_mul_f32_e32 v3, 0x3c000000, v0
	s_waitcnt lgkmcnt(0)
	v_add_f32_e32 v0, v0, v2
	v_mul_f32_e32 v0, 0x3b800000, v0
	v_cndmask_b32_e64 v0, v3, v0, s[38:39]
	v_add_f32_e32 v0, 0x358637bd, v0
	v_mul_f32_e32 v2, 0x4b800000, v0
	v_cmp_gt_f32_e32 vcc, s2, v0
	s_nop 1
	v_cndmask_b32_e32 v0, v0, v2, vcc
	v_rsq_f32_e32 v0, v0
	s_nop 0
	v_mul_f32_e32 v2, 0x45800000, v0
	v_cndmask_b32_e32 v0, v0, v2, vcc
	s_and_saveexec_b64 s[2:3], s[40:41]
	s_xor_b64 s[76:77], exec, s[2:3]
	s_cbranch_execz .LBB0_315
; __device__ __forceinline__ float siluf(float x) { return x * __builtin_amdgcn_rcpf(1.f + __builtin_amdgcn_exp2f(x * -1.44269504f)); }
; __device__ void phase_mixnorm(const KP& p, int l) {
;     ...
;     float o[16];
;     if (lane < 32) {
;       const float* nw = p.in[17] + l * 512 + lane * 16;
; #pragma unroll
;       for (int e = 0; e < 16; ++e) o[e] = x[e] * r * nw[e];
;     } else {
;       int cg0 = (lane - 32) * 16;
;       const float* nw = p.in[19] + l * 512 + cg0;
;       const bfr* gp = proj + (size_t)row * NIN + 3072 + cg0;
;       u32x4 g0 = *(const u32x4*)gp, g1 = *(const u32x4*)(gp + 8);
;       float g[16];
; #pragma unroll
;       for (int e = 0; e < 4; ++e) {
;         g[e * 2] = __uint_as_float(g0[e] << 16); g[e * 2 + 1] = __uint_as_float(g0[e] & 0xffff0000u);
;         g[8 + e * 2] = __uint_as_float(g1[e] << 16); g[8 + e * 2 + 1] = __uint_as_float(g1[e] & 0xffff0000u);
;       }
; #pragma unroll
;       for (int e = 0; e < 16; ++e) o[e] = x[e] * r * nw[e] * siluf(g[e]);
;     }
	v_readlane_b32 s2, v255, 45
	v_readlane_b32 s3, v255, 46
	v_pk_mul_f32 v[38:39], v[0:1], v[6:7] op_sel_hi:[0,1]
	v_pk_mul_f32 v[48:49], v[0:1], v[48:49] op_sel_hi:[0,1]
	v_lshl_add_u64 v[2:3], s[2:3], 0, v[26:27]
	s_mov_b64 s[2:3], 0x432a800
	v_lshl_add_u64 v[4:5], v[2:3], 0, s[2:3]
	v_add_co_u32_e32 v2, vcc, 0x432a000, v2
	v_pk_mul_f32 v[46:47], v[0:1], v[46:47] op_sel_hi:[0,1]
	s_nop 0
	v_addc_co_u32_e32 v3, vcc, 0, v3, vcc
	v_mov_b32_e32 v14, v96
	v_mov_b32_e32 v15, v97
	v_mov_b32_e32 v16, v98
	v_mov_b32_e32 v17, v99
	s_nop 0
	v_mov_b32_e32 v2, v100
	v_mov_b32_e32 v3, v101
	v_mov_b32_e32 v4, v102
	v_mov_b32_e32 v5, v103
	v_pk_mul_f32 v[44:45], v[0:1], v[44:45] op_sel_hi:[0,1]
	v_pk_mul_f32 v[40:41], v[0:1], v[40:41] op_sel_hi:[0,1]
	s_nop 0
	v_lshlrev_b32_e32 v60, 16, v14
	v_mul_f32_e32 v6, 0xbfb8aa3b, v60
	v_exp_f32_e32 v6, v6
	v_and_b32_e32 v61, 0xffff0000, v14
	v_mul_f32_e32 v14, 0xbfb8aa3b, v61
	v_exp_f32_e32 v14, v14
	v_add_f32_e32 v6, 1.0, v6
	v_rcp_f32_e32 v62, v6
	v_mov_b32_e32 v6, v76
	v_mov_b32_e32 v7, v77
	v_mov_b32_e32 v8, v78
	v_mov_b32_e32 v9, v79
	v_mov_b32_e32 v10, v72
	v_mov_b32_e32 v11, v73
	v_mov_b32_e32 v12, v74
	v_mov_b32_e32 v13, v75
	v_mov_b32_e32 v18, v68
	v_mov_b32_e32 v19, v69
	v_mov_b32_e32 v20, v70
	v_mov_b32_e32 v21, v71
	v_mov_b32_e32 v56, v64
	v_mov_b32_e32 v57, v65
	v_mov_b32_e32 v58, v66
	v_mov_b32_e32 v59, v67
	v_add_f32_e32 v14, 1.0, v14
	v_rcp_f32_e32 v63, v14
	v_lshlrev_b32_e32 v14, 16, v15
	v_mul_f32_e32 v55, 0xbfb8aa3b, v14
	v_exp_f32_e32 v55, v55
	v_and_b32_e32 v15, 0xffff0000, v15
	v_add_f32_e32 v55, 1.0, v55
	s_nop 0
	v_pk_mul_f32 v[12:13], v[40:41], v[12:13]
	s_nop 0
	v_pk_mul_f32 v[18:19], v[46:47], v[18:19]
	s_nop 0
	v_pk_mul_f32 v[38:39], v[38:39], v[56:57]
	v_pk_mul_f32 v[56:57], v[62:63], v[60:61]
	v_pk_mul_f32 v[48:49], v[48:49], v[58:59]
	v_pk_mul_f32 v[38:39], v[38:39], v[56:57]
	v_rcp_f32_e32 v56, v55
	v_mul_f32_e32 v55, 0xbfb8aa3b, v15
	v_exp_f32_e32 v55, v55
	v_pk_mul_f32 v[20:21], v[44:45], v[20:21]
	v_add_f32_e32 v55, 1.0, v55
	v_rcp_f32_e32 v57, v55
	s_nop 0
	v_pk_mul_f32 v[14:15], v[56:57], v[14:15]
	s_nop 0
	v_pk_mul_f32 v[14:15], v[48:49], v[14:15]
	v_lshlrev_b32_e32 v48, 16, v16
	v_and_b32_e32 v49, 0xffff0000, v16
	v_mul_f32_e32 v16, 0xbfb8aa3b, v48
	v_exp_f32_e32 v16, v16
	s_nop 0
	v_add_f32_e32 v16, 1.0, v16
	v_rcp_f32_e32 v56, v16
	v_mul_f32_e32 v16, 0xbfb8aa3b, v49
	v_exp_f32_e32 v16, v16
	s_nop 0
	v_add_f32_e32 v16, 1.0, v16
	v_rcp_f32_e32 v57, v16
	v_lshlrev_b32_e32 v16, 16, v17
	v_and_b32_e32 v17, 0xffff0000, v17
	v_mul_f32_e32 v44, 0xbfb8aa3b, v17
	v_pk_mul_f32 v[46:47], v[56:57], v[48:49]
	v_exp_f32_e32 v44, v44
	v_pk_mul_f32 v[18:19], v[18:19], v[46:47]
	v_mul_f32_e32 v46, 0xbfb8aa3b, v16
	v_exp_f32_e32 v46, v46
	v_add_f32_e32 v44, 1.0, v44
	v_rcp_f32_e32 v47, v44
	v_add_f32_e32 v46, 1.0, v46
	v_rcp_f32_e32 v46, v46
	s_nop 0
	v_pk_mul_f32 v[16:17], v[46:47], v[16:17]
	s_nop 0
	v_pk_mul_f32 v[16:17], v[16:17], v[20:21]
	v_pk_mul_f32 v[20:21], v[0:1], v[42:43] op_sel_hi:[0,1]
	v_lshlrev_b32_e32 v42, 16, v2
	v_and_b32_e32 v43, 0xffff0000, v2
	v_mul_f32_e32 v2, 0xbfb8aa3b, v42
	v_exp_f32_e32 v2, v2
	v_pk_mul_f32 v[10:11], v[20:21], v[10:11]
	v_add_f32_e32 v2, 1.0, v2
	v_rcp_f32_e32 v44, v2
	v_mul_f32_e32 v2, 0xbfb8aa3b, v43
	v_exp_f32_e32 v2, v2
	s_nop 0
	v_add_f32_e32 v2, 1.0, v2
	v_rcp_f32_e32 v45, v2
	v_lshlrev_b32_e32 v2, 16, v3
	v_and_b32_e32 v3, 0xffff0000, v3
	v_pk_mul_f32 v[20:21], v[44:45], v[42:43]
	s_nop 0
	v_pk_mul_f32 v[10:11], v[20:21], v[10:11]
	v_mul_f32_e32 v20, 0xbfb8aa3b, v2
	v_mul_f32_e32 v21, 0xbfb8aa3b, v3
	v_exp_f32_e32 v20, v20
	v_exp_f32_e32 v21, v21
	v_add_f32_e32 v20, 1.0, v20
	v_add_f32_e32 v21, 1.0, v21
	v_rcp_f32_e32 v20, v20
	v_rcp_f32_e32 v21, v21
	s_nop 0
	v_pk_mul_f32 v[2:3], v[20:21], v[2:3]
	v_lshlrev_b32_e32 v20, 16, v4
	v_and_b32_e32 v21, 0xffff0000, v4
	v_mul_f32_e32 v4, 0xbfb8aa3b, v20
	v_exp_f32_e32 v4, v4
	v_pk_mul_f32 v[2:3], v[2:3], v[12:13]
	v_pk_mul_f32 v[12:13], v[0:1], v[36:37] op_sel_hi:[0,1]
	v_pk_mul_f32 v[6:7], v[12:13], v[6:7]
	v_add_f32_e32 v4, 1.0, v4
	v_rcp_f32_e32 v36, v4
	v_mul_f32_e32 v4, 0xbfb8aa3b, v21
	v_exp_f32_e32 v4, v4
	s_nop 0
	v_add_f32_e32 v4, 1.0, v4
	v_rcp_f32_e32 v37, v4
	v_lshlrev_b32_e32 v4, 16, v5
	v_and_b32_e32 v5, 0xffff0000, v5
	v_pk_mul_f32 v[12:13], v[36:37], v[20:21]
	s_nop 0
	v_pk_mul_f32 v[12:13], v[12:13], v[6:7]
	v_pk_mul_f32 v[6:7], v[0:1], v[34:35] op_sel_hi:[0,1]
	v_mul_f32_e32 v0, 0xbfb8aa3b, v4
	v_exp_f32_e32 v0, v0
	v_pk_mul_f32 v[6:7], v[6:7], v[8:9]
	v_add_f32_e32 v0, 1.0, v0
	v_rcp_f32_e32 v20, v0
	v_mul_f32_e32 v0, 0xbfb8aa3b, v5
	v_exp_f32_e32 v0, v0
	s_nop 0
	v_add_f32_e32 v0, 1.0, v0
	v_rcp_f32_e32 v21, v0
	s_nop 0
	v_pk_mul_f32 v[4:5], v[20:21], v[4:5]
	s_nop 0
	v_pk_mul_f32 v[4:5], v[4:5], v[6:7]
.LBB0_315:
	s_andn2_saveexec_b64 s[76:77], s[76:77]
	s_cbranch_execz .LBB0_312
	v_mov_b32_e32 v2, v64
	v_mov_b32_e32 v3, v65
	v_mov_b32_e32 v4, v66
	v_mov_b32_e32 v5, v67
	v_mov_b32_e32 v8, v68
	v_mov_b32_e32 v9, v69
	v_mov_b32_e32 v10, v70
	v_mov_b32_e32 v11, v71
	v_mov_b32_e32 v56, v72
	v_mov_b32_e32 v57, v73
	v_mov_b32_e32 v58, v74
	v_mov_b32_e32 v59, v75
	v_mov_b32_e32 v60, v76
	v_mov_b32_e32 v61, v77
	v_mov_b32_e32 v62, v78
	v_mov_b32_e32 v63, v79
	v_pk_mul_f32 v[6:7], v[0:1], v[6:7] op_sel_hi:[0,1]
	v_pk_mul_f32 v[12:13], v[0:1], v[48:49] op_sel_hi:[0,1]
	v_pk_mul_f32 v[16:17], v[0:1], v[46:47] op_sel_hi:[0,1]
	v_pk_mul_f32 v[20:21], v[0:1], v[44:45] op_sel_hi:[0,1]
	v_pk_mul_f32 v[42:43], v[0:1], v[42:43] op_sel_hi:[0,1]
	v_pk_mul_f32 v[40:41], v[0:1], v[40:41] op_sel_hi:[0,1]
	v_pk_mul_f32 v[36:37], v[0:1], v[36:37] op_sel_hi:[0,1]
	v_pk_mul_f32 v[34:35], v[0:1], v[34:35] op_sel_hi:[0,1]
	s_nop 0
	v_pk_mul_f32 v[38:39], v[6:7], v[2:3]
	v_pk_mul_f32 v[14:15], v[12:13], v[4:5]
	s_nop 0
	v_pk_mul_f32 v[18:19], v[16:17], v[8:9]
	v_pk_mul_f32 v[16:17], v[20:21], v[10:11]
	s_nop 0
	v_pk_mul_f32 v[10:11], v[42:43], v[56:57]
	v_pk_mul_f32 v[2:3], v[40:41], v[58:59]
	s_nop 0
	v_pk_mul_f32 v[12:13], v[36:37], v[60:61]
	v_pk_mul_f32 v[4:5], v[34:35], v[62:63]
	s_branch .LBB0_312

; __device__ void phase_final(const KP& p) {
;   int tid_ = threadIdx.x; asm volatile("" : "+v"(tid_));
;   const int lane = tid_ & 63, w = tid_ >> 6;
;   const bfr* hb = (const bfr*)(p.ws + OFF_HB);
;   const float* lw = p.in[25];
;   for (int row = p.bid * 8 + w; row < T_ROWS; row += p.nblk * 8) {
;     ...
;     for (int i = 0; i < 2; ++i) {
;       int c = lane * 8 + 512 * i;
;       float4 w0 = *(const float4*)(lw + c), w1 = *(const float4*)(lw + c + 4);
.LBB0_1154:
	v_mov_b32_e32 v0, v156
	v_readlane_b32 s0, v255, 42
	s_waitcnt vmcnt(0)
	v_ashrrev_i32_e32 v2, 6, v0
	v_lshl_add_u32 v2, s0, 3, v2
	s_mov_b32 s0, 0x8400
	v_cmp_gt_i32_e32 vcc, s0, v2
	s_and_saveexec_b64 s[0:1], vcc
	s_cbranch_execz .LBB0_1165
	v_lshlrev_b32_e32 v0, 3, v0
	s_waitcnt lgkmcnt(0)
	v_and_b32_e32 v8, 0x1f8, v0
	v_readlane_b32 s2, v255, 45
	v_lshlrev_b32_e32 v0, 1, v8
	v_readlane_b32 s3, v255, 46
	v_readlane_b32 s36, v254, 1
	v_readlane_b32 s38, v254, 3
	v_lshl_add_u64 v[4:5], s[2:3], 0, v[0:1]
	v_readlane_b32 s2, v255, 43
	v_lshlrev_b32_e32 v0, 2, v8
	v_readlane_b32 s39, v254, 4
	s_mov_b32 s14, s2
	s_lshl_b32 s2, s2, 3
	v_readlane_b32 s16, v255, 49
	v_readlane_b32 s37, v254, 2
	v_lshl_add_u64 v[6:7], s[38:39], 0, v[0:1]
	v_readlane_b32 s3, v255, 44
	v_readlane_b32 s17, v255, 50
	s_add_u32 s36, s16, 0x8000000
	v_mov_b32_e32 v0, 0xffff0000
	s_addc_u32 s37, s17, 0
	v_lshl_add_u32 v14, v2, 12, v0
	s_lshl_b32 s3, s14, 15
	s_mov_b64 s[38:39], 0
	v_lshlrev_b32_e32 v8, 2, v8
	v_readlane_b32 s40, v254, 5
	v_readlane_b32 s41, v254, 6
	v_readlane_b32 s42, v254, 7
	v_readlane_b32 s43, v254, 8
	global_load_dwordx4 v[64:67], v[6:7], off
	global_load_dwordx4 v[68:71], v[6:7], off offset:16
	global_load_dwordx4 v[72:75], v[6:7], off offset:2048
	global_load_dwordx4 v[76:79], v[6:7], off offset:2064
	v_mov_b32_e32 v88, -1
	s_lshl_b32 s100, s2, 11
	s_mov_b32 s101, 0
	s_waitcnt vmcnt(0)
	s_branch .LBB0_1157

; __device__ void phase_final(const KP& p) {
;     ...
;   for (int row = p.bid * 8 + w; row < T_ROWS; row += p.nblk * 8) {
;     float* dst;
;     if (row < SROW0) {
;       int s = row / PROW, pos = row % PROW;
;       if (pos < 16 || pos >= PLEN) continue;
;       dst = p.out + O_YP + ((size_t)s * 4096 + (pos - 16)) * DM;
;     } else dst = p.out + O_YS + (size_t)(row - SROW0) * DM;
;     float x[16];
;     float ss = 0.f;
; #pragma unroll
;     for (int i = 0; i < 2; ++i) {
;       u32x4 v = *(const u32x4*)(hb + (size_t)row * DM + lane * 8 + 512 * i);
; #pragma unroll
;       for (int e = 0; e < 4; ++e) {
;         float a = __uint_as_float(v[e] << 16), b = __uint_as_float(v[e] & 0xffff0000u);
;         x[i * 8 + e * 2] = a; x[i * 8 + e * 2 + 1] = b;
;         ss += a * a + b * b;
;       }
;     }
;     ss = wave_sum(ss);
;     float r = rsqrtf(ss * (1.f / DM) + EPSF);
; #pragma unroll
;     for (int i = 0; i < 2; ++i) {
;       int c = lane * 8 + 512 * i;
;       float4 w0 = *(const float4*)(lw + c), w1 = *(const float4*)(lw + c + 4);
;       float4 o0 = make_float4(x[i * 8 + 0] * r * w0.x, x[i * 8 + 1] * r * w0.y, x[i * 8 + 2] * r * w0.z, x[i * 8 + 3] * r * w0.w);
;       float4 o1 = make_float4(x[i * 8 + 4] * r * w1.x, x[i * 8 + 5] * r * w1.y, x[i * 8 + 6] * r * w1.z, x[i * 8 + 7] * r * w1.w);
;       *(float4*)(dst + c) = o0; *(float4*)(dst + c + 4) = o1;
;     }
.LBB0_1164:
	v_ashrrev_i32_e32 v3, 31, v2
	v_lshlrev_b64 v[12:13], 11, v[2:3]
	v_lshl_add_u64 v[12:13], v[4:5], 0, v[12:13]
	v_cmp_eq_u32_e32 vcc, v2, v88
	s_and_b64 vcc, exec, vcc
	s_cbranch_vccz .Lfin_miss
	s_waitcnt vmcnt(4)
	s_branch .Lfin_have
.Lfin_miss:
	global_load_dwordx4 v[80:83], v[12:13], off
	global_load_dwordx4 v[84:87], v[12:13], off offset:1024
	s_waitcnt vmcnt(0)
.Lfin_have:
	v_mov_b32_e32 v16, v80
	v_mov_b32_e32 v17, v81
	v_mov_b32_e32 v18, v82
	v_mov_b32_e32 v19, v83
	v_mov_b32_e32 v20, v84
	v_mov_b32_e32 v21, v85
	v_mov_b32_e32 v22, v86
	v_mov_b32_e32 v23, v87
	v_mov_b32_e32 v24, v68
	v_mov_b32_e32 v25, v69
	v_mov_b32_e32 v26, v70
	v_mov_b32_e32 v27, v71
	v_mov_b32_e32 v28, v64
	v_mov_b32_e32 v29, v65
	v_mov_b32_e32 v30, v66
	v_mov_b32_e32 v31, v67
	v_add_u32_e32 v88, s2, v2
	v_lshl_add_u64 v[90:91], v[12:13], 0, s[100:101]
	global_load_dwordx4 v[80:83], v[90:91], off
	global_load_dwordx4 v[84:87], v[90:91], off offset:1024
	v_and_b32_e32 v0, 64, v164
	v_xor_b32_e32 v3, 32, v164
	v_add_u32_e32 v0, 64, v0
	v_cmp_lt_i32_e32 vcc, v3, v0
	s_mov_b32 s14, 0x800000
	s_nop 0
	v_lshlrev_b32_e32 v12, 16, v16
	v_and_b32_e32 v13, 0xffff0000, v16
	v_lshlrev_b32_e32 v16, 16, v17
	v_and_b32_e32 v17, 0xffff0000, v17
	v_lshlrev_b32_e32 v32, 16, v18
	v_and_b32_e32 v33, 0xffff0000, v18
	v_lshlrev_b32_e32 v34, 16, v20
	v_and_b32_e32 v35, 0xffff0000, v20
	v_lshlrev_b32_e32 v36, 16, v21
	v_and_b32_e32 v37, 0xffff0000, v21
	v_lshlrev_b32_e32 v38, 16, v22
	v_and_b32_e32 v39, 0xffff0000, v22
	v_lshlrev_b32_e32 v40, 16, v23
	v_and_b32_e32 v41, 0xffff0000, v23
	v_pk_mul_f32 v[20:21], v[12:13], v[12:13]
	v_pk_mul_f32 v[22:23], v[16:17], v[16:17]
	v_lshlrev_b32_e32 v18, 16, v19
	v_and_b32_e32 v19, 0xffff0000, v19
	v_pk_mul_f32 v[42:43], v[32:33], v[32:33]
	v_add_f32_e32 v9, v22, v23
	v_add_f32_e32 v15, v20, v21
	v_pk_mul_f32 v[44:45], v[18:19], v[18:19]
	v_mov_b32_e32 v48, v37
	v_mov_b32_e32 v49, v35
	v_add_f32_e32 v42, v42, v43
	v_add_f32_e32 v9, v15, v9
	v_mov_b32_e32 v46, v36
	v_mov_b32_e32 v47, v34
	v_pk_mul_f32 v[48:49], v[48:49], v[48:49]
	v_add_f32_e32 v43, v44, v45
	v_add_f32_e32 v9, v42, v9
	v_mov_b32_e32 v52, v41
	v_mov_b32_e32 v53, v39
	v_pk_fma_f32 v[20:21], v[46:47], v[46:47], v[48:49]
	v_add_f32_e32 v9, v43, v9
	v_mov_b32_e32 v50, v40
	v_mov_b32_e32 v51, v38
	v_pk_mul_f32 v[52:53], v[52:53], v[52:53]
	v_add_f32_e32 v9, v21, v9
	v_pk_fma_f32 v[22:23], v[50:51], v[50:51], v[52:53]
	v_add_f32_e32 v9, v20, v9
	v_cndmask_b32_e32 v3, v164, v3, vcc
	v_add_f32_e32 v9, v23, v9
	v_lshlrev_b32_e32 v3, 2, v3
	v_add_f32_e32 v9, v22, v9
	ds_bpermute_b32 v3, v3, v9
	v_xor_b32_e32 v15, 16, v164
	v_cmp_lt_i32_e32 vcc, v15, v0
	s_waitcnt lgkmcnt(0)
	v_add_f32_e32 v3, v9, v3
	v_cndmask_b32_e32 v15, v164, v15, vcc
	v_lshlrev_b32_e32 v15, 2, v15
	ds_bpermute_b32 v9, v15, v3
	v_xor_b32_e32 v15, 8, v164
	v_cmp_lt_i32_e32 vcc, v15, v0
	s_waitcnt lgkmcnt(0)
	v_add_f32_e32 v3, v3, v9
	v_cndmask_b32_e32 v15, v164, v15, vcc
	v_lshlrev_b32_e32 v15, 2, v15
	ds_bpermute_b32 v9, v15, v3
	v_xor_b32_e32 v15, 4, v164
	v_cmp_lt_i32_e32 vcc, v15, v0
	s_waitcnt lgkmcnt(0)
	v_add_f32_e32 v3, v3, v9
	v_cndmask_b32_e32 v15, v164, v15, vcc
	v_lshlrev_b32_e32 v15, 2, v15
	ds_bpermute_b32 v9, v15, v3
	v_xor_b32_e32 v15, 2, v164
	v_cmp_lt_i32_e32 vcc, v15, v0
	s_waitcnt lgkmcnt(0)
	v_add_f32_e32 v3, v3, v9
	v_cndmask_b32_e32 v15, v164, v15, vcc
	v_lshlrev_b32_e32 v15, 2, v15
	ds_bpermute_b32 v9, v15, v3
	v_xor_b32_e32 v15, 1, v164
	v_cmp_lt_i32_e32 vcc, v15, v0
	s_waitcnt lgkmcnt(0)
	v_add_f32_e32 v3, v3, v9
	v_cndmask_b32_e32 v0, v164, v15, vcc
	v_lshlrev_b32_e32 v0, 2, v0
	ds_bpermute_b32 v0, v0, v3
	v_mov_b32_e32 v9, v1
	v_lshl_add_u64 v[42:43], v[10:11], 0, v[8:9]
	s_waitcnt lgkmcnt(0)
	v_add_f32_e32 v0, v3, v0
	v_fmamk_f32 v0, v0, 0x3a800000, v162
	v_mul_f32_e32 v3, 0x4b800000, v0
	v_cmp_gt_f32_e32 vcc, s14, v0
	s_nop 1
	v_cndmask_b32_e32 v0, v0, v3, vcc
	v_rsq_f32_e32 v0, v0
	s_nop 0
	v_mul_f32_e32 v3, 0x45800000, v0
	v_cndmask_b32_e32 v0, v0, v3, vcc
	v_pk_mul_f32 v[12:13], v[0:1], v[12:13] op_sel_hi:[0,1]
	v_pk_mul_f32 v[20:21], v[0:1], v[16:17] op_sel_hi:[0,1]
	v_pk_mul_f32 v[22:23], v[0:1], v[32:33] op_sel_hi:[0,1]
	v_pk_mul_f32 v[32:33], v[0:1], v[18:19] op_sel_hi:[0,1]
	v_pk_mul_f32 v[16:17], v[28:29], v[12:13]
	v_pk_mul_f32 v[18:19], v[30:31], v[20:21]
	v_pk_mul_f32 v[20:21], v[24:25], v[22:23]
	v_pk_mul_f32 v[22:23], v[26:27], v[32:33]
	global_store_dwordx4 v[42:43], v[16:19], off
	global_store_dwordx4 v[42:43], v[20:23], off offset:16
	v_mov_b32_e32 v16, v72
	v_mov_b32_e32 v17, v73
	v_mov_b32_e32 v18, v74
	v_mov_b32_e32 v19, v75
	s_nop 0
	v_mov_b32_e32 v20, v76
	v_mov_b32_e32 v21, v77
	v_mov_b32_e32 v22, v78
	v_mov_b32_e32 v23, v79
	v_pk_mul_f32 v[12:13], v[0:1], v[34:35] op_sel_hi:[0,1]
	v_pk_mul_f32 v[24:25], v[0:1], v[36:37] op_sel_hi:[0,1]
	v_pk_mul_f32 v[26:27], v[0:1], v[38:39] op_sel_hi:[0,1]
	v_pk_mul_f32 v[28:29], v[0:1], v[40:41] op_sel_hi:[0,1]
	s_nop 0
	v_pk_mul_f32 v[16:17], v[16:17], v[12:13]
	v_pk_mul_f32 v[18:19], v[24:25], v[18:19]
	s_nop 0
	v_pk_mul_f32 v[20:21], v[26:27], v[20:21]
	v_pk_mul_f32 v[22:23], v[28:29], v[22:23]
	global_store_dwordx4 v[42:43], v[16:19], off offset:2048
	global_store_dwordx4 v[42:43], v[20:23], off offset:2064
	s_branch .LBB0_1156
